# v3 + ProjB epilogue: hssq atomics deferred to the end of the epilogue (vmcnt waits re-derived)
# speedup vs baseline: 1.0012x; 1.0012x over previous
; __device__ __forceinline__ float shx(float v, int lane, int mask) { return __int_as_float(__builtin_amdgcn_ds_bpermute((lane ^ mask) << 2, __float_as_int(v))); }
;     __device__ __forceinline__ void operator()(const AccT& acc, const Unit& u, int wr, int wc, int fr, int fq) const {
;     ...
;         for (int idx = 0; idx < 8; ++idx) {
;             const int ai = idx >> 2, m = idx & 3, rofs = ai * 128 + m * 16;
;             const int row = row0 + rofs; const float rs = rsqrtf(rsn[idx & 1] * (1.f / 1024.f) + EPS);
;             if (idx + 2 < 8) rsn[idx & 1] = ssq[row0 + ((idx + 2) >> 2) * 128 + ((idx + 2) & 3) * 16];
;             float v1[8], v2[8];
; #pragma unroll
;             for (int n = 0; n < 2; ++n)
; #pragma unroll
;                 for (int j = 0; j < 4; ++j) { v1[n * 4 + j] = acc[ai][0][m][n][j] * rs; v2[n * 4 + j] = acc[ai][1][m][n][j] * rs; }
;             if (rope) {
;                 float s = 0.f;
; #pragma unroll
;                 for (int e = 0; e < 8; ++e) s += v1[e] * v1[e] + v2[e] * v2[e];
;                 s += shx(s, LANE_, 16); s += shx(s, LANE_, 32);
;                 if (fq == 0) atomicAdd(hssq + (size_t)row * 24 + seg * 12 + head, s);
.LBB0_547:
	v_lshlrev_b32_e32 v51, 8, v182
	v_and_b32_e32 v188, 0x1fcf00, v51
	v_cndmask_b32_e64 v51, 0, 1, s[28:29]
	v_lshl_add_u64 v[186:187], v[170:171], 0, v[188:189]
	v_cmp_ne_u32_e64 s[4:5], 1, v51
	s_mov_b64 s[58:59], s[4:5]
	s_andn2_b64 vcc, exec, s[28:29]
	v_lshl_add_u64 v[184:185], v[172:173], 0, v[188:189]
	s_cbranch_vccnz .LBB0_549
	global_load_dwordx4 v[64:67], v[186:187], off offset:16
	global_load_dwordx4 v[68:71], v[186:187], off
	global_load_dwordx4 v[88:91], v[184:185], off offset:16
	global_load_dwordx4 v[92:95], v[184:185], off
.LBB0_549:
	global_load_dword v51, v[198:199], off offset:128
	s_waitcnt vmcnt(0)
	v_fmamk_f32 v55, v179, 0x3a800000, v226
	v_mul_f32_e32 v179, 0x4b800000, v55
	v_cmp_gt_f32_e32 vcc, s33, v55
	s_lshl_b32 s23, s23, 1
	s_or_b32 s28, s23, s44
	v_cndmask_b32_e32 v55, v55, v179, vcc
	v_rsq_f32_e32 v55, v55
	s_mul_i32 s30, s21, 12
	s_ashr_i32 s31, s30, 31
	s_ashr_i32 s29, s28, 31
	v_mul_f32_e32 v179, 0x45800000, v55
	v_cndmask_b32_e32 v188, v55, v179, vcc
	v_pk_mul_f32 v[200:201], v[148:149], v[188:189] op_sel_hi:[1,0]
	v_mul_f32_e32 v148, v146, v188
	v_mov_b32_e32 v146, v155
	v_pk_mul_f32 v[204:205], v[156:157], v[188:189] op_sel_hi:[1,0]
	v_pk_mul_f32 v[202:203], v[158:159], v[188:189] op_sel_hi:[1,0]
	v_pk_mul_f32 v[156:157], v[150:151], v[188:189] op_sel_hi:[1,0]
	v_pk_mul_f32 v[158:159], v[152:153], v[188:189] op_sel_hi:[1,0]
	v_pk_mul_f32 v[150:151], v[144:145], v[188:189] op_sel_hi:[1,0]
	v_mul_f32_e32 v152, v154, v188
	s_and_b64 vcc, exec, s[4:5]
	v_pk_mul_f32 v[144:145], v[146:147], v[188:189] op_sel_hi:[1,0]
	s_cbranch_vccnz .LBB0_553
	v_pk_mul_f32 v[146:147], v[200:201], v[200:201]
	v_pk_mul_f32 v[154:155], v[156:157], v[156:157]
	v_pk_fma_f32 v[146:147], v[204:205], v[204:205], v[146:147]
	v_pk_fma_f32 v[154:155], v[202:203], v[202:203], v[154:155]
	v_add_f32_e32 v55, v146, v147
	v_pk_mul_f32 v[210:211], v[150:151], v[150:151]
	v_add_f32_e32 v55, v154, v55
	v_pk_fma_f32 v[210:211], v[158:159], v[158:159], v[210:211]
	v_add_f32_e32 v55, v155, v55
	v_add_f32_e32 v55, v210, v55
	v_mul_f32_e32 v146, v148, v148
	v_add_f32_e32 v55, v211, v55
	v_fmac_f32_e32 v146, v152, v152
	v_add_f32_e32 v55, v146, v55
	v_pk_mul_f32 v[146:147], v[144:145], v[144:145]
	s_nop 0
	v_add_f32_e32 v146, v146, v147
	v_add_f32_e32 v55, v146, v55
	ds_bpermute_b32 v146, v207, v55
	s_waitcnt lgkmcnt(0)
	v_add_f32_e32 v55, v55, v146
	ds_bpermute_b32 v146, v208, v55
	s_and_saveexec_b64 s[34:35], s[0:1]
	s_cbranch_execz .LBB0_552
	s_waitcnt lgkmcnt(0)
	v_add_f32_e32 v55, v55, v146
	v_mov_b64_e32 v[146:147], s[14:15]
	v_mad_i64_i32 v[146:147], s[50:51], v182, s63, v[146:147]
	v_lshl_add_u64 v[146:147], s[30:31], 2, v[146:147]
	v_lshl_add_u64 v[146:147], s[28:29], 2, v[146:147]
	v_mov_b32_e32 v218, v55

; __device__ __forceinline__ unsigned pk2(float lo, float hi) { f32x2 v = {lo, hi}; bf2_t b = __builtin_convertvector(v, bf2_t); return __builtin_bit_cast(unsigned, b); }
; #define EPI_SCHED() do {} while (0)
;     __device__ __forceinline__ void operator()(const AccT& acc, const Unit& u, int wr, int wc, int fr, int fq) const {
;     ...
;         for (int idx = 0; idx < 8; ++idx) {
;             const int ai = idx >> 2, m = idx & 3, rofs = ai * 128 + m * 16;
;             const int row = row0 + rofs; const float rs = rsqrtf(rsn[idx & 1] * (1.f / 1024.f) + EPS);
;             if (idx + 2 < 8) rsn[idx & 1] = ssq[row0 + ((idx + 2) >> 2) * 128 + ((idx + 2) & 3) * 16];
;             float v1[8], v2[8];
; #pragma unroll
;             for (int n = 0; n < 2; ++n)
; #pragma unroll
;                 for (int j = 0; j < 4; ++j) { v1[n * 4 + j] = acc[ai][0][m][n][j] * rs; v2[n * 4 + j] = acc[ai][1][m][n][j] * rs; }
;             if (rope) {
;                 float s = 0.f;
; #pragma unroll
;                 for (int e = 0; e < 8; ++e) s += v1[e] * v1[e] + v2[e] * v2[e];
;                 s += shx(s, LANE_, 16); s += shx(s, LANE_, 32);
;                 if (fq == 0) atomicAdd(hssq + (size_t)row * 24 + seg * 12 + head, s);
; #pragma unroll
;                 for (int e = 0; e < 8; ++e) {
;                     const float cs = e < 4 ? tca[e & 3] : tcb[e & 3], sn = e < 4 ? tsa[e & 3] : tsb[e & 3];
;                     const float y1 = v1[e] * (e < 4 ? g1a[e & 3] : g1b[e & 3]), y2 = v2[e] * (e < 4 ? g2a[e & 3] : g2b[e & 3]);
;                     v1[e] = y1 * cs - y2 * sn; v2[e] = y2 * cs + y1 * sn;
;                 }
;                 EPI_SCHED();
;                 if (idx + 1 < 8) { const int ro = ((idx + 1) >> 2) * 128 + ((idx + 1) & 3) * 16;
;                     tca = *(const f32x4*)(cb0 + ro * 64); tcb = *(const f32x4*)(cb0 + ro * 64 + 4); tsa = *(const f32x4*)(sb0 + ro * 64); tsb = *(const f32x4*)(sb0 + ro * 64 + 4); }
;                 EPI_SCHED();
;             }
;             u32x4 w1, w2; w1.x = pk2(v1[0], v1[1]); w1.y = pk2(v1[2], v1[3]); w1.z = pk2(v1[4], v1[5]); w1.w = pk2(v1[6], v1[7]);
;             w2.x = pk2(v2[0], v2[1]); w2.y = pk2(v2[2], v2[3]); w2.z = pk2(v2[4], v2[5]); w2.w = pk2(v2[6], v2[7]);
;             bf16_t* p = base + (size_t)row * ATW + head * 128 + c0;
;             *(u32x4*)p = w1; *(u32x4*)(p + 64) = w2;
.LBB0_554:
	s_mul_hi_i32 s23, s21, 0x6000000
	s_mul_i32 s21, s21, 0x6000000
	s_add_u32 s21, s46, s21
	s_addc_u32 s23, s47, s23
	s_lshl_b32 s34, s28, 7
	s_ashr_i32 s35, s34, 31
	s_lshl_b64 s[34:35], s[34:35], 1
	s_add_u32 s34, s21, s34
	s_addc_u32 s35, s23, s35
	v_mov_b32_e32 v179, v189
	v_lshl_add_u64 v[144:145], s[34:35], 0, v[178:179]
	v_cvt_pk_bf16_f32 v210, v204, v205
	v_cvt_pk_bf16_f32 v211, v202, v203
	v_cvt_pk_bf16_f32 v212, v158, v159
	v_cvt_pk_bf16_f32 v213, v152, v153
	v_mad_i64_i32 v[146:147], s[34:35], v182, s80, v[144:145]
	v_cvt_pk_bf16_f32 v152, v200, v201
	v_cvt_pk_bf16_f32 v153, v156, v157
	v_cvt_pk_bf16_f32 v154, v150, v151
	v_cvt_pk_bf16_f32 v155, v148, v149
	global_store_dwordx4 v[146:147], v[210:213], off
	global_store_dwordx4 v[146:147], v[152:155], off offset:128
	global_load_dword v150, v[198:199], off offset:192
	v_fmamk_f32 v55, v183, 0x3a800000, v226
	v_mul_f32_e32 v146, 0x4b800000, v55
	v_cmp_gt_f32_e32 vcc, s33, v55
	s_nop 1
	v_cndmask_b32_e32 v55, v55, v146, vcc
	v_rsq_f32_e32 v146, v55
	v_or_b32_e32 v55, 16, v182
	v_mul_f32_e32 v147, 0x45800000, v146
	v_cndmask_b32_e32 v152, v146, v147, vcc
	v_pk_mul_f32 v[148:149], v[140:141], v[152:153] op_sel_hi:[1,0]
	v_pk_mul_f32 v[140:141], v[132:133], v[152:153] op_sel_hi:[1,0]
	v_pk_mul_f32 v[132:133], v[128:129], v[152:153] op_sel_hi:[1,0]
	v_mul_f32_e32 v128, v130, v152
	v_mov_b32_e32 v130, v139
	v_pk_mul_f32 v[146:147], v[142:143], v[152:153] op_sel_hi:[1,0]
	v_pk_mul_f32 v[134:135], v[134:135], v[152:153] op_sel_hi:[1,0]
	v_pk_mul_f32 v[142:143], v[136:137], v[152:153] op_sel_hi:[1,0]
	v_mul_f32_e32 v136, v138, v152
	s_and_b64 vcc, exec, s[4:5]
	v_pk_mul_f32 v[130:131], v[130:131], v[152:153] op_sel_hi:[1,0]
	s_cbranch_vccnz .LBB0_558
	v_pk_mul_f32 v[138:139], v[140:141], v[140:141]
	v_pk_mul_f32 v[152:153], v[134:135], v[134:135]
	v_pk_fma_f32 v[138:139], v[148:149], v[148:149], v[138:139]
	v_pk_fma_f32 v[152:153], v[146:147], v[146:147], v[152:153]
	v_add_f32_e32 v129, v138, v139
	v_pk_mul_f32 v[154:155], v[132:133], v[132:133]
	v_add_f32_e32 v129, v152, v129
	v_pk_fma_f32 v[154:155], v[142:143], v[142:143], v[154:155]
	v_add_f32_e32 v129, v153, v129
	v_add_f32_e32 v129, v154, v129
	v_mul_f32_e32 v137, v128, v128
	v_add_f32_e32 v129, v155, v129
	v_fmac_f32_e32 v137, v136, v136
	v_pk_mul_f32 v[138:139], v[130:131], v[130:131]
	v_add_f32_e32 v129, v137, v129
	v_add_f32_e32 v137, v138, v139
	v_add_f32_e32 v129, v137, v129
	ds_bpermute_b32 v137, v207, v129
	s_waitcnt lgkmcnt(0)
	v_add_f32_e32 v129, v129, v137
	ds_bpermute_b32 v137, v208, v129
	s_and_saveexec_b64 s[34:35], s[0:1]
	s_cbranch_execz .LBB0_557
	v_mov_b64_e32 v[138:139], s[14:15]
	v_mad_i64_i32 v[138:139], s[50:51], v55, s63, v[138:139]
	v_lshl_add_u64 v[138:139], s[30:31], 2, v[138:139]
	s_waitcnt lgkmcnt(0)
	v_add_f32_e32 v129, v129, v137
	v_lshl_add_u64 v[138:139], s[28:29], 2, v[138:139]
	v_mov_b32_e32 v219, v129
.LBB0_557:
	s_or_b64 exec, exec, s[34:35]
	v_mul_f32_e32 v129, v136, v54
	v_mul_f32_e32 v128, v128, v50
	s_waitcnt vmcnt(4)
	v_mul_f32_e32 v136, v129, v66
	s_waitcnt vmcnt(2)
	v_mul_f32_e32 v156, v128, v90
	v_mul_f32_e32 v128, v128, v66
	v_mul_f32_e32 v158, v129, v90
	v_pk_mul_f32 v[130:131], v[130:131], v[180:181]
	v_mov_b32_e32 v66, v91
	v_mov_b32_e32 v90, v67
	v_pk_mul_f32 v[200:201], v[130:131], v[66:67]
	v_pk_mul_f32 v[66:67], v[130:131], v[90:91]
	v_pk_mul_f32 v[132:133], v[132:133], v[48:49]
	s_waitcnt lgkmcnt(0)
	v_mov_b32_e32 v137, v66
	v_add_co_u32_e32 v66, vcc, s64, v186
	v_mov_b32_e32 v157, v67
	s_nop 0
	v_addc_co_u32_e32 v67, vcc, 0, v187, vcc
	v_pk_mul_f32 v[140:141], v[140:141], v[56:57]
	v_pk_mul_f32 v[134:135], v[134:135], v[58:59]
	v_pk_mul_f32 v[142:143], v[142:143], v[52:53]
	v_pk_mul_f32 v[154:155], v[132:133], v[88:89]
	v_pk_mul_f32 v[132:133], v[132:133], v[64:65]
	s_mov_b64 s[34:35], 0x2000
	v_add_co_u32_e32 v90, vcc, s64, v184
	v_pk_mul_f32 v[138:139], v[148:149], v[60:61]
	v_pk_mul_f32 v[148:149], v[140:141], v[92:93]
	v_pk_mul_f32 v[140:141], v[140:141], v[68:69]
	v_pk_mul_f32 v[146:147], v[146:147], v[62:63]
	v_pk_mul_f32 v[152:153], v[134:135], v[94:95]
	v_pk_mul_f32 v[134:135], v[134:135], v[70:71]
	v_pk_fma_f32 v[132:133], v[142:143], v[88:89], v[132:133]
	v_pk_fma_f32 v[142:143], v[142:143], v[64:65], v[154:155] neg_lo:[0,0,1] neg_hi:[0,0,1]
	v_lshl_add_u64 v[64:65], v[186:187], 0, s[34:35]
	v_lshl_add_u64 v[88:89], v[184:185], 0, s[34:35]
	v_addc_co_u32_e32 v91, vcc, 0, v185, vcc
	v_pk_fma_f32 v[140:141], v[138:139], v[92:93], v[140:141]
	v_pk_fma_f32 v[134:135], v[146:147], v[94:95], v[134:135]
	v_pk_fma_f32 v[148:149], v[138:139], v[68:69], v[148:149] neg_lo:[0,0,1] neg_hi:[0,0,1]
	v_pk_fma_f32 v[146:147], v[146:147], v[70:71], v[152:153] neg_lo:[0,0,1] neg_hi:[0,0,1]
	global_load_dwordx4 v[68:71], v[66:67], off
	s_nop 0
	global_load_dwordx4 v[64:67], v[64:65], off offset:16
	s_nop 0
	global_load_dwordx4 v[92:95], v[90:91], off
	s_nop 0
	global_load_dwordx4 v[88:91], v[88:89], off offset:16
	v_mov_b32_e32 v159, v200
	v_mov_b32_e32 v129, v201
	v_pk_add_f32 v[128:129], v[158:159], v[128:129]
	v_pk_add_f32 v[136:137], v[136:137], v[156:157] neg_lo:[0,1] neg_hi:[0,1]
	s_branch .LBB0_559

; __device__ __forceinline__ unsigned pk2(float lo, float hi) { f32x2 v = {lo, hi}; bf2_t b = __builtin_convertvector(v, bf2_t); return __builtin_bit_cast(unsigned, b); }
; #define EPI_SCHED() do {} while (0)
;     __device__ __forceinline__ void operator()(const AccT& acc, const Unit& u, int wr, int wc, int fr, int fq) const {
;     ...
;         for (int idx = 0; idx < 8; ++idx) {
;             const int ai = idx >> 2, m = idx & 3, rofs = ai * 128 + m * 16;
;             const int row = row0 + rofs; const float rs = rsqrtf(rsn[idx & 1] * (1.f / 1024.f) + EPS);
;             if (idx + 2 < 8) rsn[idx & 1] = ssq[row0 + ((idx + 2) >> 2) * 128 + ((idx + 2) & 3) * 16];
;             float v1[8], v2[8];
; #pragma unroll
;             for (int n = 0; n < 2; ++n)
; #pragma unroll
;                 for (int j = 0; j < 4; ++j) { v1[n * 4 + j] = acc[ai][0][m][n][j] * rs; v2[n * 4 + j] = acc[ai][1][m][n][j] * rs; }
;             if (rope) {
;                 float s = 0.f;
; #pragma unroll
;                 for (int e = 0; e < 8; ++e) s += v1[e] * v1[e] + v2[e] * v2[e];
;                 s += shx(s, LANE_, 16); s += shx(s, LANE_, 32);
;                 if (fq == 0) atomicAdd(hssq + (size_t)row * 24 + seg * 12 + head, s);
; #pragma unroll
;                 for (int e = 0; e < 8; ++e) {
;                     const float cs = e < 4 ? tca[e & 3] : tcb[e & 3], sn = e < 4 ? tsa[e & 3] : tsb[e & 3];
;                     const float y1 = v1[e] * (e < 4 ? g1a[e & 3] : g1b[e & 3]), y2 = v2[e] * (e < 4 ? g2a[e & 3] : g2b[e & 3]);
;                     v1[e] = y1 * cs - y2 * sn; v2[e] = y2 * cs + y1 * sn;
;                 }
;                 EPI_SCHED();
;                 if (idx + 1 < 8) { const int ro = ((idx + 1) >> 2) * 128 + ((idx + 1) & 3) * 16;
;                     tca = *(const f32x4*)(cb0 + ro * 64); tcb = *(const f32x4*)(cb0 + ro * 64 + 4); tsa = *(const f32x4*)(sb0 + ro * 64); tsb = *(const f32x4*)(sb0 + ro * 64 + 4); }
;                 EPI_SCHED();
;             }
;             u32x4 w1, w2; w1.x = pk2(v1[0], v1[1]); w1.y = pk2(v1[2], v1[3]); w1.z = pk2(v1[4], v1[5]); w1.w = pk2(v1[6], v1[7]);
;             w2.x = pk2(v2[0], v2[1]); w2.y = pk2(v2[2], v2[3]); w2.z = pk2(v2[4], v2[5]); w2.w = pk2(v2[6], v2[7]);
;             bf16_t* p = base + (size_t)row * ATW + head * 128 + c0;
;             *(u32x4*)p = w1; *(u32x4*)(p + 64) = w2;
.LBB0_559:
	v_cvt_pk_bf16_f32 v152, v148, v149
	v_cvt_pk_bf16_f32 v153, v146, v147
	v_cvt_pk_bf16_f32 v154, v142, v143
	v_cvt_pk_bf16_f32 v155, v136, v137
	v_cvt_pk_bf16_f32 v132, v132, v133
	v_cvt_pk_bf16_f32 v133, v128, v129
	v_mad_i64_i32 v[128:129], s[34:35], v55, s80, v[144:145]
	v_cvt_pk_bf16_f32 v130, v140, v141
	v_cvt_pk_bf16_f32 v131, v134, v135
	global_store_dwordx4 v[128:129], v[152:155], off
	global_store_dwordx4 v[128:129], v[130:133], off offset:128
	global_load_dword v55, v[198:199], off offset:512
	v_fmamk_f32 v51, v51, 0x3a800000, v226
	v_mul_f32_e32 v128, 0x4b800000, v51
	v_cmp_gt_f32_e32 vcc, s33, v51
	s_nop 1
	v_cndmask_b32_e32 v51, v51, v128, vcc
	v_rsq_f32_e32 v128, v51
	v_or_b32_e32 v51, 32, v182
	v_mul_f32_e32 v129, 0x45800000, v128
	v_cndmask_b32_e32 v132, v128, v129, vcc
	v_pk_mul_f32 v[130:131], v[124:125], v[132:133] op_sel_hi:[1,0]
	v_pk_mul_f32 v[124:125], v[116:117], v[132:133] op_sel_hi:[1,0]
	v_pk_mul_f32 v[116:117], v[112:113], v[132:133] op_sel_hi:[1,0]
	v_mul_f32_e32 v112, v114, v132
	v_mov_b32_e32 v114, v123
	v_pk_mul_f32 v[128:129], v[126:127], v[132:133] op_sel_hi:[1,0]
	v_pk_mul_f32 v[118:119], v[118:119], v[132:133] op_sel_hi:[1,0]
	v_pk_mul_f32 v[126:127], v[120:121], v[132:133] op_sel_hi:[1,0]
	v_mul_f32_e32 v120, v122, v132
	s_and_b64 vcc, exec, s[4:5]
	v_pk_mul_f32 v[114:115], v[114:115], v[132:133] op_sel_hi:[1,0]
	s_cbranch_vccnz .LBB0_563
	v_pk_mul_f32 v[122:123], v[124:125], v[124:125]
	v_pk_mul_f32 v[132:133], v[118:119], v[118:119]
	v_pk_fma_f32 v[122:123], v[130:131], v[130:131], v[122:123]
	v_pk_fma_f32 v[132:133], v[128:129], v[128:129], v[132:133]
	v_add_f32_e32 v113, v122, v123
	v_pk_mul_f32 v[134:135], v[116:117], v[116:117]
	v_add_f32_e32 v113, v132, v113
	v_pk_fma_f32 v[134:135], v[126:127], v[126:127], v[134:135]
	v_add_f32_e32 v113, v133, v113
	v_add_f32_e32 v113, v134, v113
	v_mul_f32_e32 v121, v112, v112
	v_add_f32_e32 v113, v135, v113
	v_fmac_f32_e32 v121, v120, v120
	v_pk_mul_f32 v[122:123], v[114:115], v[114:115]
	v_add_f32_e32 v113, v121, v113
	v_add_f32_e32 v121, v122, v123
	v_add_f32_e32 v113, v121, v113
	ds_bpermute_b32 v121, v207, v113
	s_waitcnt lgkmcnt(0)
	v_add_f32_e32 v113, v113, v121
	ds_bpermute_b32 v121, v208, v113
	s_and_saveexec_b64 s[34:35], s[0:1]
	s_cbranch_execz .LBB0_562
	v_mov_b64_e32 v[122:123], s[14:15]
	v_mad_i64_i32 v[122:123], s[50:51], v51, s63, v[122:123]
	v_lshl_add_u64 v[122:123], s[30:31], 2, v[122:123]
	s_waitcnt lgkmcnt(0)
	v_add_f32_e32 v113, v113, v121
	v_lshl_add_u64 v[122:123], s[28:29], 2, v[122:123]
	v_mov_b32_e32 v220, v113
.LBB0_562:
	s_or_b64 exec, exec, s[34:35]
	v_mul_f32_e32 v113, v54, v120
	v_mul_f32_e32 v112, v50, v112
	s_waitcnt vmcnt(4)
	v_mul_f32_e32 v120, v113, v66
	s_waitcnt vmcnt(2)
	v_mul_f32_e32 v136, v112, v90
	v_mul_f32_e32 v112, v112, v66
	v_mul_f32_e32 v138, v113, v90
	v_pk_mul_f32 v[114:115], v[180:181], v[114:115]
	v_mov_b32_e32 v66, v91
	v_mov_b32_e32 v90, v67
	v_pk_mul_f32 v[140:141], v[114:115], v[66:67]
	v_pk_mul_f32 v[66:67], v[114:115], v[90:91]
	v_pk_mul_f32 v[116:117], v[48:49], v[116:117]
	s_waitcnt lgkmcnt(0)
	v_mov_b32_e32 v121, v66
	v_add_co_u32_e32 v66, vcc, s79, v186
	v_mov_b32_e32 v137, v67
	s_nop 0
	v_addc_co_u32_e32 v67, vcc, 0, v187, vcc
	v_pk_mul_f32 v[124:125], v[56:57], v[124:125]
	v_pk_mul_f32 v[118:119], v[58:59], v[118:119]
	v_pk_mul_f32 v[126:127], v[52:53], v[126:127]
	v_pk_mul_f32 v[134:135], v[116:117], v[88:89]
	v_pk_mul_f32 v[116:117], v[116:117], v[64:65]
	s_mov_b64 s[34:35], 0x3000
	v_add_co_u32_e32 v90, vcc, s79, v184
	v_pk_mul_f32 v[122:123], v[60:61], v[130:131]
	v_pk_mul_f32 v[130:131], v[124:125], v[92:93]
	v_pk_mul_f32 v[124:125], v[124:125], v[68:69]
	v_pk_mul_f32 v[128:129], v[62:63], v[128:129]
	v_pk_mul_f32 v[132:133], v[118:119], v[94:95]
	v_pk_mul_f32 v[118:119], v[118:119], v[70:71]
	v_pk_fma_f32 v[116:117], v[126:127], v[88:89], v[116:117]
	v_pk_fma_f32 v[126:127], v[126:127], v[64:65], v[134:135] neg_lo:[0,0,1] neg_hi:[0,0,1]
	v_lshl_add_u64 v[64:65], v[186:187], 0, s[34:35]
	v_lshl_add_u64 v[88:89], v[184:185], 0, s[34:35]
	v_addc_co_u32_e32 v91, vcc, 0, v185, vcc
	v_pk_fma_f32 v[124:125], v[122:123], v[92:93], v[124:125]
	v_pk_fma_f32 v[118:119], v[128:129], v[94:95], v[118:119]
	v_pk_fma_f32 v[130:131], v[122:123], v[68:69], v[130:131] neg_lo:[0,0,1] neg_hi:[0,0,1]
	v_pk_fma_f32 v[128:129], v[128:129], v[70:71], v[132:133] neg_lo:[0,0,1] neg_hi:[0,0,1]
	global_load_dwordx4 v[68:71], v[66:67], off
	s_nop 0
	global_load_dwordx4 v[64:67], v[64:65], off offset:16
	s_nop 0
	global_load_dwordx4 v[92:95], v[90:91], off
	s_nop 0
	global_load_dwordx4 v[88:91], v[88:89], off offset:16
	v_mov_b32_e32 v139, v140
	v_mov_b32_e32 v113, v141
	v_pk_add_f32 v[112:113], v[138:139], v[112:113]
	v_pk_add_f32 v[120:121], v[120:121], v[136:137] neg_lo:[0,1] neg_hi:[0,1]
	s_branch .LBB0_564

; __device__ __forceinline__ unsigned pk2(float lo, float hi) { f32x2 v = {lo, hi}; bf2_t b = __builtin_convertvector(v, bf2_t); return __builtin_bit_cast(unsigned, b); }
; #define EPI_SCHED() do {} while (0)
;     __device__ __forceinline__ void operator()(const AccT& acc, const Unit& u, int wr, int wc, int fr, int fq) const {
;     ...
;         for (int idx = 0; idx < 8; ++idx) {
;             const int ai = idx >> 2, m = idx & 3, rofs = ai * 128 + m * 16;
;             const int row = row0 + rofs; const float rs = rsqrtf(rsn[idx & 1] * (1.f / 1024.f) + EPS);
;             if (idx + 2 < 8) rsn[idx & 1] = ssq[row0 + ((idx + 2) >> 2) * 128 + ((idx + 2) & 3) * 16];
;             float v1[8], v2[8];
; #pragma unroll
;             for (int n = 0; n < 2; ++n)
; #pragma unroll
;                 for (int j = 0; j < 4; ++j) { v1[n * 4 + j] = acc[ai][0][m][n][j] * rs; v2[n * 4 + j] = acc[ai][1][m][n][j] * rs; }
;             if (rope) {
;                 float s = 0.f;
; #pragma unroll
;                 for (int e = 0; e < 8; ++e) s += v1[e] * v1[e] + v2[e] * v2[e];
;                 s += shx(s, LANE_, 16); s += shx(s, LANE_, 32);
;                 if (fq == 0) atomicAdd(hssq + (size_t)row * 24 + seg * 12 + head, s);
; #pragma unroll
;                 for (int e = 0; e < 8; ++e) {
;                     const float cs = e < 4 ? tca[e & 3] : tcb[e & 3], sn = e < 4 ? tsa[e & 3] : tsb[e & 3];
;                     const float y1 = v1[e] * (e < 4 ? g1a[e & 3] : g1b[e & 3]), y2 = v2[e] * (e < 4 ? g2a[e & 3] : g2b[e & 3]);
;                     v1[e] = y1 * cs - y2 * sn; v2[e] = y2 * cs + y1 * sn;
;                 }
;                 EPI_SCHED();
;                 if (idx + 1 < 8) { const int ro = ((idx + 1) >> 2) * 128 + ((idx + 1) & 3) * 16;
;                     tca = *(const f32x4*)(cb0 + ro * 64); tcb = *(const f32x4*)(cb0 + ro * 64 + 4); tsa = *(const f32x4*)(sb0 + ro * 64); tsb = *(const f32x4*)(sb0 + ro * 64 + 4); }
;                 EPI_SCHED();
;             }
;             u32x4 w1, w2; w1.x = pk2(v1[0], v1[1]); w1.y = pk2(v1[2], v1[3]); w1.z = pk2(v1[4], v1[5]); w1.w = pk2(v1[6], v1[7]);
;             w2.x = pk2(v2[0], v2[1]); w2.y = pk2(v2[2], v2[3]); w2.z = pk2(v2[4], v2[5]); w2.w = pk2(v2[6], v2[7]);
;             bf16_t* p = base + (size_t)row * ATW + head * 128 + c0;
;             *(u32x4*)p = w1; *(u32x4*)(p + 64) = w2;
.LBB0_564:
	v_cvt_pk_bf16_f32 v130, v130, v131
	v_cvt_pk_bf16_f32 v131, v128, v129
	v_cvt_pk_bf16_f32 v132, v126, v127
	v_cvt_pk_bf16_f32 v133, v120, v121
	v_cvt_pk_bf16_f32 v116, v116, v117
	v_cvt_pk_bf16_f32 v117, v112, v113
	v_mad_i64_i32 v[112:113], s[34:35], v51, s80, v[144:145]
	v_cvt_pk_bf16_f32 v114, v124, v125
	v_cvt_pk_bf16_f32 v115, v118, v119
	global_store_dwordx4 v[112:113], v[130:133], off
	global_store_dwordx4 v[112:113], v[114:117], off offset:128
	global_load_dword v51, v[198:199], off offset:576
	s_waitcnt vmcnt(6)
	v_fmamk_f32 v112, v150, 0x3a800000, v226
	v_mul_f32_e32 v113, 0x4b800000, v112
	v_cmp_gt_f32_e32 vcc, s33, v112
	v_or_b32_e32 v116, 48, v182
	s_nop 0
	v_cndmask_b32_e32 v112, v112, v113, vcc
	v_rsq_f32_e32 v112, v112
	s_nop 0
	v_mul_f32_e32 v113, 0x45800000, v112
	v_cndmask_b32_e32 v118, v112, v113, vcc
	v_pk_mul_f32 v[114:115], v[108:109], v[118:119] op_sel_hi:[1,0]
	v_pk_mul_f32 v[108:109], v[100:101], v[118:119] op_sel_hi:[1,0]
	v_pk_mul_f32 v[100:101], v[96:97], v[118:119] op_sel_hi:[1,0]
	v_mul_f32_e32 v96, v98, v118
	v_mov_b32_e32 v98, v107
	v_pk_mul_f32 v[112:113], v[110:111], v[118:119] op_sel_hi:[1,0]
	v_pk_mul_f32 v[102:103], v[102:103], v[118:119] op_sel_hi:[1,0]
	v_pk_mul_f32 v[110:111], v[104:105], v[118:119] op_sel_hi:[1,0]
	v_mul_f32_e32 v104, v106, v118
	s_and_b64 vcc, exec, s[4:5]
	v_pk_mul_f32 v[98:99], v[98:99], v[118:119] op_sel_hi:[1,0]
	s_cbranch_vccnz .LBB0_568
	v_pk_mul_f32 v[106:107], v[108:109], v[108:109]
	v_pk_mul_f32 v[118:119], v[102:103], v[102:103]
	v_pk_fma_f32 v[106:107], v[114:115], v[114:115], v[106:107]
	v_pk_fma_f32 v[118:119], v[112:113], v[112:113], v[118:119]
	v_add_f32_e32 v97, v106, v107
	v_pk_mul_f32 v[120:121], v[100:101], v[100:101]
	v_add_f32_e32 v97, v118, v97
	v_pk_fma_f32 v[120:121], v[110:111], v[110:111], v[120:121]
	v_add_f32_e32 v97, v119, v97
	v_add_f32_e32 v97, v120, v97
	v_mul_f32_e32 v105, v96, v96
	v_add_f32_e32 v97, v121, v97
	v_fmac_f32_e32 v105, v104, v104
	v_pk_mul_f32 v[106:107], v[98:99], v[98:99]
	v_add_f32_e32 v97, v105, v97
	v_add_f32_e32 v105, v106, v107
	v_add_f32_e32 v97, v105, v97
	ds_bpermute_b32 v105, v207, v97
	s_waitcnt lgkmcnt(0)
	v_add_f32_e32 v97, v97, v105
	ds_bpermute_b32 v105, v208, v97
	s_and_saveexec_b64 s[34:35], s[0:1]
	s_cbranch_execz .LBB0_567
	v_mov_b64_e32 v[106:107], s[14:15]
	v_mad_i64_i32 v[106:107], s[50:51], v116, s63, v[106:107]
	v_lshl_add_u64 v[106:107], s[30:31], 2, v[106:107]
	s_waitcnt lgkmcnt(0)
	v_add_f32_e32 v97, v97, v105
	v_lshl_add_u64 v[106:107], s[28:29], 2, v[106:107]
	v_mov_b32_e32 v221, v97
.LBB0_567:
	s_or_b64 exec, exec, s[34:35]
	v_mul_f32_e32 v97, v54, v104
	v_mul_f32_e32 v96, v50, v96
	s_waitcnt vmcnt(4)
	v_mul_f32_e32 v104, v97, v66
	s_waitcnt vmcnt(2)
	v_mul_f32_e32 v122, v96, v90
	v_mul_f32_e32 v96, v96, v66
	v_mul_f32_e32 v124, v97, v90
	v_pk_mul_f32 v[98:99], v[180:181], v[98:99]
	v_mov_b32_e32 v66, v91
	v_mov_b32_e32 v90, v67
	v_pk_mul_f32 v[126:127], v[98:99], v[66:67]
	v_pk_mul_f32 v[66:67], v[98:99], v[90:91]
	v_pk_mul_f32 v[100:101], v[48:49], v[100:101]
	s_waitcnt lgkmcnt(0)
	v_mov_b32_e32 v105, v66
	v_add_co_u32_e32 v66, vcc, s85, v186
	v_mov_b32_e32 v123, v67
	s_nop 0
	v_addc_co_u32_e32 v67, vcc, 0, v187, vcc
	v_pk_mul_f32 v[108:109], v[56:57], v[108:109]
	v_pk_mul_f32 v[102:103], v[58:59], v[102:103]
	v_pk_mul_f32 v[110:111], v[52:53], v[110:111]
	v_pk_mul_f32 v[120:121], v[100:101], v[88:89]
	v_pk_mul_f32 v[100:101], v[100:101], v[64:65]
	s_mov_b64 s[34:35], 0x8000
	v_add_co_u32_e32 v90, vcc, s85, v184
	v_pk_mul_f32 v[106:107], v[60:61], v[114:115]
	v_pk_mul_f32 v[114:115], v[108:109], v[92:93]
	v_pk_mul_f32 v[108:109], v[108:109], v[68:69]
	v_pk_mul_f32 v[112:113], v[62:63], v[112:113]
	v_pk_mul_f32 v[118:119], v[102:103], v[94:95]
	v_pk_mul_f32 v[102:103], v[102:103], v[70:71]
	v_pk_fma_f32 v[100:101], v[110:111], v[88:89], v[100:101]
	v_pk_fma_f32 v[110:111], v[110:111], v[64:65], v[120:121] neg_lo:[0,0,1] neg_hi:[0,0,1]
	v_lshl_add_u64 v[64:65], v[186:187], 0, s[34:35]
	v_lshl_add_u64 v[88:89], v[184:185], 0, s[34:35]
	v_addc_co_u32_e32 v91, vcc, 0, v185, vcc
	v_pk_fma_f32 v[108:109], v[106:107], v[92:93], v[108:109]
	v_pk_fma_f32 v[102:103], v[112:113], v[94:95], v[102:103]
	v_pk_fma_f32 v[114:115], v[106:107], v[68:69], v[114:115] neg_lo:[0,0,1] neg_hi:[0,0,1]
	v_pk_fma_f32 v[112:113], v[112:113], v[70:71], v[118:119] neg_lo:[0,0,1] neg_hi:[0,0,1]
	global_load_dwordx4 v[68:71], v[66:67], off
	s_nop 0
	global_load_dwordx4 v[64:67], v[64:65], off offset:16
	s_nop 0
	global_load_dwordx4 v[92:95], v[90:91], off
	s_nop 0
	global_load_dwordx4 v[88:91], v[88:89], off offset:16
	v_mov_b32_e32 v125, v126
	v_mov_b32_e32 v97, v127
	v_pk_add_f32 v[96:97], v[124:125], v[96:97]
	v_pk_add_f32 v[104:105], v[104:105], v[122:123] neg_lo:[0,1] neg_hi:[0,1]
	s_branch .LBB0_569

; __device__ __forceinline__ unsigned pk2(float lo, float hi) { f32x2 v = {lo, hi}; bf2_t b = __builtin_convertvector(v, bf2_t); return __builtin_bit_cast(unsigned, b); }
; #define EPI_SCHED() do {} while (0)
;     __device__ __forceinline__ void operator()(const AccT& acc, const Unit& u, int wr, int wc, int fr, int fq) const {
;     ...
;         for (int idx = 0; idx < 8; ++idx) {
;             const int ai = idx >> 2, m = idx & 3, rofs = ai * 128 + m * 16;
;             const int row = row0 + rofs; const float rs = rsqrtf(rsn[idx & 1] * (1.f / 1024.f) + EPS);
;             if (idx + 2 < 8) rsn[idx & 1] = ssq[row0 + ((idx + 2) >> 2) * 128 + ((idx + 2) & 3) * 16];
;             float v1[8], v2[8];
; #pragma unroll
;             for (int n = 0; n < 2; ++n)
; #pragma unroll
;                 for (int j = 0; j < 4; ++j) { v1[n * 4 + j] = acc[ai][0][m][n][j] * rs; v2[n * 4 + j] = acc[ai][1][m][n][j] * rs; }
;             if (rope) {
;                 float s = 0.f;
; #pragma unroll
;                 for (int e = 0; e < 8; ++e) s += v1[e] * v1[e] + v2[e] * v2[e];
;                 s += shx(s, LANE_, 16); s += shx(s, LANE_, 32);
;                 if (fq == 0) atomicAdd(hssq + (size_t)row * 24 + seg * 12 + head, s);
; #pragma unroll
;                 for (int e = 0; e < 8; ++e) {
;                     const float cs = e < 4 ? tca[e & 3] : tcb[e & 3], sn = e < 4 ? tsa[e & 3] : tsb[e & 3];
;                     const float y1 = v1[e] * (e < 4 ? g1a[e & 3] : g1b[e & 3]), y2 = v2[e] * (e < 4 ? g2a[e & 3] : g2b[e & 3]);
;                     v1[e] = y1 * cs - y2 * sn; v2[e] = y2 * cs + y1 * sn;
;                 }
;                 EPI_SCHED();
;                 if (idx + 1 < 8) { const int ro = ((idx + 1) >> 2) * 128 + ((idx + 1) & 3) * 16;
;                     tca = *(const f32x4*)(cb0 + ro * 64); tcb = *(const f32x4*)(cb0 + ro * 64 + 4); tsa = *(const f32x4*)(sb0 + ro * 64); tsb = *(const f32x4*)(sb0 + ro * 64 + 4); }
;                 EPI_SCHED();
;             }
;             u32x4 w1, w2; w1.x = pk2(v1[0], v1[1]); w1.y = pk2(v1[2], v1[3]); w1.z = pk2(v1[4], v1[5]); w1.w = pk2(v1[6], v1[7]);
;             w2.x = pk2(v2[0], v2[1]); w2.y = pk2(v2[2], v2[3]); w2.z = pk2(v2[4], v2[5]); w2.w = pk2(v2[6], v2[7]);
;             bf16_t* p = base + (size_t)row * ATW + head * 128 + c0;
;             *(u32x4*)p = w1; *(u32x4*)(p + 64) = w2;
.LBB0_569:
	v_cvt_pk_bf16_f32 v118, v114, v115
	v_cvt_pk_bf16_f32 v119, v112, v113
	v_cvt_pk_bf16_f32 v120, v110, v111
	v_cvt_pk_bf16_f32 v121, v104, v105
	v_cvt_pk_bf16_f32 v98, v108, v109
	v_cvt_pk_bf16_f32 v100, v100, v101
	v_cvt_pk_bf16_f32 v101, v96, v97
	v_mad_i64_i32 v[96:97], s[34:35], v116, s80, v[144:145]
	v_cvt_pk_bf16_f32 v99, v102, v103
	global_store_dwordx4 v[96:97], v[118:121], off
	global_store_dwordx4 v[96:97], v[98:101], off offset:128
	s_waitcnt vmcnt(5)
	v_fmamk_f32 v55, v55, 0x3a800000, v226
	v_cmp_gt_f32_e32 vcc, s33, v55
	v_add_u32_e32 v98, 0x80, v182
	v_ashrrev_i32_e32 v99, 31, v98
	v_lshl_add_u64 v[96:97], v[98:99], 2, s[12:13]
	global_load_dword v99, v[96:97], off offset:128
	v_mul_f32_e32 v100, 0x4b800000, v55
	v_cndmask_b32_e32 v55, v55, v100, vcc
	v_rsq_f32_e32 v55, v55
	s_nop 0
	v_mul_f32_e32 v100, 0x45800000, v55
	v_cndmask_b32_e32 v104, v55, v100, vcc
	v_pk_mul_f32 v[102:103], v[84:85], v[104:105] op_sel_hi:[1,0]
	v_pk_mul_f32 v[84:85], v[76:77], v[104:105] op_sel_hi:[1,0]
	v_pk_mul_f32 v[76:77], v[72:73], v[104:105] op_sel_hi:[1,0]
	v_mul_f32_e32 v72, v74, v104
	v_mov_b32_e32 v74, v83
	v_pk_mul_f32 v[100:101], v[86:87], v[104:105] op_sel_hi:[1,0]
	v_pk_mul_f32 v[78:79], v[78:79], v[104:105] op_sel_hi:[1,0]
	v_pk_mul_f32 v[86:87], v[80:81], v[104:105] op_sel_hi:[1,0]
	v_mul_f32_e32 v80, v82, v104
	s_and_b64 vcc, exec, s[4:5]
	v_pk_mul_f32 v[74:75], v[74:75], v[104:105] op_sel_hi:[1,0]
	s_cbranch_vccnz .LBB0_573
	v_pk_mul_f32 v[82:83], v[84:85], v[84:85]
	v_pk_mul_f32 v[104:105], v[78:79], v[78:79]
	v_pk_fma_f32 v[82:83], v[102:103], v[102:103], v[82:83]
	v_pk_fma_f32 v[104:105], v[100:101], v[100:101], v[104:105]
	v_add_f32_e32 v55, v82, v83
	v_pk_mul_f32 v[106:107], v[76:77], v[76:77]
	v_add_f32_e32 v55, v104, v55
	v_pk_fma_f32 v[106:107], v[86:87], v[86:87], v[106:107]
	v_add_f32_e32 v55, v105, v55
	v_add_f32_e32 v55, v106, v55
	v_mul_f32_e32 v73, v72, v72
	v_add_f32_e32 v55, v107, v55
	v_fmac_f32_e32 v73, v80, v80
	v_pk_mul_f32 v[82:83], v[74:75], v[74:75]
	v_add_f32_e32 v55, v73, v55
	v_add_f32_e32 v73, v82, v83
	v_add_f32_e32 v55, v73, v55
	ds_bpermute_b32 v73, v207, v55
	s_waitcnt lgkmcnt(0)
	v_add_f32_e32 v55, v55, v73
	ds_bpermute_b32 v73, v208, v55
	s_and_saveexec_b64 s[34:35], s[0:1]
	s_cbranch_execz .LBB0_572
	v_mov_b64_e32 v[82:83], s[14:15]
	v_mad_i64_i32 v[82:83], s[50:51], v98, s63, v[82:83]
	v_lshl_add_u64 v[82:83], s[30:31], 2, v[82:83]
	s_waitcnt lgkmcnt(0)
	v_add_f32_e32 v55, v55, v73
	v_lshl_add_u64 v[82:83], s[28:29], 2, v[82:83]
	v_mov_b32_e32 v222, v55
.LBB0_572:
	s_or_b64 exec, exec, s[34:35]
	v_mul_f32_e32 v55, v54, v80
	v_mul_f32_e32 v72, v50, v72
	s_waitcnt vmcnt(4)
	v_mul_f32_e32 v80, v55, v66
	s_waitcnt vmcnt(2)
	v_mul_f32_e32 v108, v72, v90
	v_mul_f32_e32 v72, v72, v66
	v_mul_f32_e32 v110, v55, v90
	v_pk_mul_f32 v[74:75], v[180:181], v[74:75]
	v_mov_b32_e32 v66, v91
	v_mov_b32_e32 v90, v67
	v_pk_mul_f32 v[112:113], v[74:75], v[66:67]
	v_pk_mul_f32 v[66:67], v[74:75], v[90:91]
	v_pk_mul_f32 v[84:85], v[56:57], v[84:85]
	v_mov_b32_e32 v81, v66
	v_add_co_u32_e32 v66, vcc, s86, v186
	v_pk_mul_f32 v[82:83], v[60:61], v[102:103]
	v_pk_mul_f32 v[102:103], v[84:85], v[92:93]
	v_pk_mul_f32 v[84:85], v[84:85], v[68:69]
	v_pk_mul_f32 v[76:77], v[48:49], v[76:77]
	v_mov_b32_e32 v109, v67
	v_addc_co_u32_e32 v67, vcc, 0, v187, vcc
	v_pk_mul_f32 v[78:79], v[58:59], v[78:79]
	v_pk_mul_f32 v[86:87], v[52:53], v[86:87]
	v_pk_mul_f32 v[106:107], v[76:77], v[88:89]
	v_pk_mul_f32 v[76:77], v[76:77], v[64:65]
	v_pk_fma_f32 v[84:85], v[82:83], v[92:93], v[84:85]
	v_pk_fma_f32 v[102:103], v[82:83], v[68:69], v[102:103] neg_lo:[0,0,1] neg_hi:[0,0,1]
	s_mov_b64 s[34:35], 0x9000
	v_add_co_u32_e32 v82, vcc, s86, v184
	v_pk_mul_f32 v[100:101], v[62:63], v[100:101]
	v_pk_mul_f32 v[104:105], v[78:79], v[94:95]
	v_pk_mul_f32 v[78:79], v[78:79], v[70:71]
	v_pk_fma_f32 v[76:77], v[86:87], v[88:89], v[76:77]
	v_pk_fma_f32 v[86:87], v[86:87], v[64:65], v[106:107] neg_lo:[0,0,1] neg_hi:[0,0,1]
	v_lshl_add_u64 v[64:65], v[186:187], 0, s[34:35]
	v_addc_co_u32_e32 v83, vcc, 0, v185, vcc
	v_pk_fma_f32 v[78:79], v[100:101], v[94:95], v[78:79]
	v_pk_fma_f32 v[100:101], v[100:101], v[70:71], v[104:105] neg_lo:[0,0,1] neg_hi:[0,0,1]
	global_load_dwordx4 v[68:71], v[66:67], off
	s_nop 0
	global_load_dwordx4 v[64:67], v[64:65], off offset:16
	v_lshl_add_u64 v[74:75], v[184:185], 0, s[34:35]
	global_load_dwordx4 v[92:95], v[82:83], off
	global_load_dwordx4 v[88:91], v[74:75], off offset:16
	v_mov_b32_e32 v111, v112
	s_waitcnt lgkmcnt(0)
	v_mov_b32_e32 v73, v113
	v_pk_add_f32 v[72:73], v[110:111], v[72:73]
	v_pk_add_f32 v[80:81], v[80:81], v[108:109] neg_lo:[0,1] neg_hi:[0,1]
	s_branch .LBB0_574

; __device__ __forceinline__ unsigned pk2(float lo, float hi) { f32x2 v = {lo, hi}; bf2_t b = __builtin_convertvector(v, bf2_t); return __builtin_bit_cast(unsigned, b); }
; #define EPI_SCHED() do {} while (0)
;     __device__ __forceinline__ void operator()(const AccT& acc, const Unit& u, int wr, int wc, int fr, int fq) const {
;     ...
;         for (int idx = 0; idx < 8; ++idx) {
;             const int ai = idx >> 2, m = idx & 3, rofs = ai * 128 + m * 16;
;             const int row = row0 + rofs; const float rs = rsqrtf(rsn[idx & 1] * (1.f / 1024.f) + EPS);
;             if (idx + 2 < 8) rsn[idx & 1] = ssq[row0 + ((idx + 2) >> 2) * 128 + ((idx + 2) & 3) * 16];
;             float v1[8], v2[8];
; #pragma unroll
;             for (int n = 0; n < 2; ++n)
; #pragma unroll
;                 for (int j = 0; j < 4; ++j) { v1[n * 4 + j] = acc[ai][0][m][n][j] * rs; v2[n * 4 + j] = acc[ai][1][m][n][j] * rs; }
;             if (rope) {
;                 float s = 0.f;
; #pragma unroll
;                 for (int e = 0; e < 8; ++e) s += v1[e] * v1[e] + v2[e] * v2[e];
;                 s += shx(s, LANE_, 16); s += shx(s, LANE_, 32);
;                 if (fq == 0) atomicAdd(hssq + (size_t)row * 24 + seg * 12 + head, s);
; #pragma unroll
;                 for (int e = 0; e < 8; ++e) {
;                     const float cs = e < 4 ? tca[e & 3] : tcb[e & 3], sn = e < 4 ? tsa[e & 3] : tsb[e & 3];
;                     const float y1 = v1[e] * (e < 4 ? g1a[e & 3] : g1b[e & 3]), y2 = v2[e] * (e < 4 ? g2a[e & 3] : g2b[e & 3]);
;                     v1[e] = y1 * cs - y2 * sn; v2[e] = y2 * cs + y1 * sn;
;                 }
;                 EPI_SCHED();
;                 if (idx + 1 < 8) { const int ro = ((idx + 1) >> 2) * 128 + ((idx + 1) & 3) * 16;
;                     tca = *(const f32x4*)(cb0 + ro * 64); tcb = *(const f32x4*)(cb0 + ro * 64 + 4); tsa = *(const f32x4*)(sb0 + ro * 64); tsb = *(const f32x4*)(sb0 + ro * 64 + 4); }
;                 EPI_SCHED();
;             }
;             u32x4 w1, w2; w1.x = pk2(v1[0], v1[1]); w1.y = pk2(v1[2], v1[3]); w1.z = pk2(v1[4], v1[5]); w1.w = pk2(v1[6], v1[7]);
;             w2.x = pk2(v2[0], v2[1]); w2.y = pk2(v2[2], v2[3]); w2.z = pk2(v2[4], v2[5]); w2.w = pk2(v2[6], v2[7]);
;             bf16_t* p = base + (size_t)row * ATW + head * 128 + c0;
;             *(u32x4*)p = w1; *(u32x4*)(p + 64) = w2;
.LBB0_574:
	v_cvt_pk_bf16_f32 v102, v102, v103
	v_cvt_pk_bf16_f32 v103, v100, v101
	v_cvt_pk_bf16_f32 v104, v86, v87
	v_cvt_pk_bf16_f32 v105, v80, v81
	v_cvt_pk_bf16_f32 v76, v76, v77
	v_cvt_pk_bf16_f32 v77, v72, v73
	v_mad_i64_i32 v[72:73], s[34:35], v98, s80, v[144:145]
	v_cvt_pk_bf16_f32 v74, v84, v85
	v_cvt_pk_bf16_f32 v75, v78, v79
	global_store_dwordx4 v[72:73], v[102:105], off
	global_store_dwordx4 v[72:73], v[74:77], off offset:128
	global_load_dword v55, v[96:97], off offset:192
	s_waitcnt vmcnt(6)
	v_fmamk_f32 v51, v51, 0x3a800000, v226
	v_mul_f32_e32 v72, 0x4b800000, v51
	v_cmp_gt_f32_e32 vcc, s33, v51
	s_nop 1
	v_cndmask_b32_e32 v51, v51, v72, vcc
	v_rsq_f32_e32 v72, v51
	v_add_u32_e32 v51, 0x90, v182
	v_mul_f32_e32 v73, 0x45800000, v72
	v_cndmask_b32_e32 v76, v72, v73, vcc
	v_pk_mul_f32 v[74:75], v[44:45], v[76:77] op_sel_hi:[1,0]
	v_pk_mul_f32 v[44:45], v[36:37], v[76:77] op_sel_hi:[1,0]
	v_pk_mul_f32 v[36:37], v[32:33], v[76:77] op_sel_hi:[1,0]
	v_mul_f32_e32 v32, v34, v76
	v_mov_b32_e32 v34, v43
	v_pk_mul_f32 v[72:73], v[46:47], v[76:77] op_sel_hi:[1,0]
	v_pk_mul_f32 v[38:39], v[38:39], v[76:77] op_sel_hi:[1,0]
	v_pk_mul_f32 v[46:47], v[40:41], v[76:77] op_sel_hi:[1,0]
	v_mul_f32_e32 v40, v42, v76
	s_and_b64 vcc, exec, s[4:5]
	v_pk_mul_f32 v[34:35], v[34:35], v[76:77] op_sel_hi:[1,0]
	s_cbranch_vccnz .LBB0_578
	v_pk_mul_f32 v[42:43], v[44:45], v[44:45]
	v_pk_mul_f32 v[76:77], v[38:39], v[38:39]
	v_pk_fma_f32 v[42:43], v[74:75], v[74:75], v[42:43]
	v_pk_fma_f32 v[76:77], v[72:73], v[72:73], v[76:77]
	v_add_f32_e32 v33, v42, v43
	v_pk_mul_f32 v[78:79], v[36:37], v[36:37]
	v_add_f32_e32 v33, v76, v33
	v_pk_fma_f32 v[78:79], v[46:47], v[46:47], v[78:79]
	v_add_f32_e32 v33, v77, v33
	v_add_f32_e32 v33, v78, v33
	v_mul_f32_e32 v41, v32, v32
	v_add_f32_e32 v33, v79, v33
	v_fmac_f32_e32 v41, v40, v40
	v_pk_mul_f32 v[42:43], v[34:35], v[34:35]
	v_add_f32_e32 v33, v41, v33
	v_add_f32_e32 v41, v42, v43
	v_add_f32_e32 v33, v41, v33
	ds_bpermute_b32 v41, v207, v33
	s_waitcnt lgkmcnt(0)
	v_add_f32_e32 v33, v33, v41
	ds_bpermute_b32 v41, v208, v33
	s_and_saveexec_b64 s[34:35], s[0:1]
	s_cbranch_execz .LBB0_577
	v_mov_b64_e32 v[42:43], s[14:15]
	v_mad_i64_i32 v[42:43], s[50:51], v51, s63, v[42:43]
	v_lshl_add_u64 v[42:43], s[30:31], 2, v[42:43]
	s_waitcnt lgkmcnt(0)
	v_add_f32_e32 v33, v33, v41
	v_lshl_add_u64 v[42:43], s[28:29], 2, v[42:43]
	v_mov_b32_e32 v223, v33
.LBB0_577:
	s_or_b64 exec, exec, s[34:35]
	v_pk_mul_f32 v[44:45], v[56:57], v[44:45]
	v_pk_mul_f32 v[42:43], v[60:61], v[74:75]
	s_waitcnt vmcnt(3)
	v_pk_mul_f32 v[74:75], v[44:45], v[92:93]
	v_pk_mul_f32 v[44:45], v[44:45], v[68:69]
	v_mul_f32_e32 v33, v54, v40
	v_mul_f32_e32 v32, v50, v32
	v_pk_mul_f32 v[38:39], v[58:59], v[38:39]
	v_pk_mul_f32 v[36:37], v[48:49], v[36:37]
	v_mul_f32_e32 v40, v33, v66
	s_waitcnt vmcnt(2)
	v_mul_f32_e32 v80, v32, v90
	v_mul_f32_e32 v32, v32, v66
	v_mul_f32_e32 v82, v33, v90
	v_pk_mul_f32 v[34:35], v[180:181], v[34:35]
	v_mov_b32_e32 v66, v91
	v_pk_fma_f32 v[44:45], v[42:43], v[92:93], v[44:45]
	v_mov_b32_e32 v90, v67
	v_pk_fma_f32 v[74:75], v[42:43], v[68:69], v[74:75] neg_lo:[0,0,1] neg_hi:[0,0,1]
	v_add_co_u32_e32 v42, vcc, s65, v186
	v_pk_mul_f32 v[72:73], v[62:63], v[72:73]
	v_pk_mul_f32 v[76:77], v[38:39], v[94:95]
	v_pk_mul_f32 v[38:39], v[38:39], v[70:71]
	v_pk_mul_f32 v[46:47], v[52:53], v[46:47]
	v_pk_mul_f32 v[78:79], v[36:37], v[88:89]
	v_pk_mul_f32 v[36:37], v[36:37], v[64:65]
	v_pk_mul_f32 v[84:85], v[34:35], v[66:67]
	v_pk_mul_f32 v[34:35], v[34:35], v[90:91]
	s_mov_b64 s[34:35], 0xa000
	v_addc_co_u32_e32 v43, vcc, 0, v187, vcc
	v_pk_fma_f32 v[38:39], v[72:73], v[94:95], v[38:39]
	v_pk_fma_f32 v[36:37], v[46:47], v[88:89], v[36:37]
	s_waitcnt lgkmcnt(0)
	v_mov_b32_e32 v41, v34
	v_mov_b32_e32 v81, v35
	v_pk_fma_f32 v[72:73], v[72:73], v[70:71], v[76:77] neg_lo:[0,0,1] neg_hi:[0,0,1]
	v_pk_fma_f32 v[46:47], v[46:47], v[64:65], v[78:79] neg_lo:[0,0,1] neg_hi:[0,0,1]
	v_lshl_add_u64 v[34:35], v[186:187], 0, s[34:35]
	global_load_dwordx4 v[68:71], v[42:43], off
	global_load_dwordx4 v[64:67], v[34:35], off offset:16
	v_add_co_u32_e32 v42, vcc, s65, v184
	v_lshl_add_u64 v[34:35], v[184:185], 0, s[34:35]
	s_nop 0
	v_addc_co_u32_e32 v43, vcc, 0, v185, vcc
	global_load_dwordx4 v[92:95], v[42:43], off
	global_load_dwordx4 v[88:91], v[34:35], off offset:16
	v_mov_b32_e32 v83, v84
	v_mov_b32_e32 v33, v85
	v_pk_add_f32 v[32:33], v[82:83], v[32:33]
	v_pk_add_f32 v[40:41], v[40:41], v[80:81] neg_lo:[0,1] neg_hi:[0,1]
	s_branch .LBB0_579

; __device__ __forceinline__ unsigned pk2(float lo, float hi) { f32x2 v = {lo, hi}; bf2_t b = __builtin_convertvector(v, bf2_t); return __builtin_bit_cast(unsigned, b); }
; #define EPI_SCHED() do {} while (0)
;     __device__ __forceinline__ void operator()(const AccT& acc, const Unit& u, int wr, int wc, int fr, int fq) const {
;     ...
;         for (int idx = 0; idx < 8; ++idx) {
;             const int ai = idx >> 2, m = idx & 3, rofs = ai * 128 + m * 16;
;             const int row = row0 + rofs; const float rs = rsqrtf(rsn[idx & 1] * (1.f / 1024.f) + EPS);
;             if (idx + 2 < 8) rsn[idx & 1] = ssq[row0 + ((idx + 2) >> 2) * 128 + ((idx + 2) & 3) * 16];
;             float v1[8], v2[8];
; #pragma unroll
;             for (int n = 0; n < 2; ++n)
; #pragma unroll
;                 for (int j = 0; j < 4; ++j) { v1[n * 4 + j] = acc[ai][0][m][n][j] * rs; v2[n * 4 + j] = acc[ai][1][m][n][j] * rs; }
;             if (rope) {
;                 float s = 0.f;
; #pragma unroll
;                 for (int e = 0; e < 8; ++e) s += v1[e] * v1[e] + v2[e] * v2[e];
;                 s += shx(s, LANE_, 16); s += shx(s, LANE_, 32);
;                 if (fq == 0) atomicAdd(hssq + (size_t)row * 24 + seg * 12 + head, s);
; #pragma unroll
;                 for (int e = 0; e < 8; ++e) {
;                     const float cs = e < 4 ? tca[e & 3] : tcb[e & 3], sn = e < 4 ? tsa[e & 3] : tsb[e & 3];
;                     const float y1 = v1[e] * (e < 4 ? g1a[e & 3] : g1b[e & 3]), y2 = v2[e] * (e < 4 ? g2a[e & 3] : g2b[e & 3]);
;                     v1[e] = y1 * cs - y2 * sn; v2[e] = y2 * cs + y1 * sn;
;                 }
;                 EPI_SCHED();
;                 if (idx + 1 < 8) { const int ro = ((idx + 1) >> 2) * 128 + ((idx + 1) & 3) * 16;
;                     tca = *(const f32x4*)(cb0 + ro * 64); tcb = *(const f32x4*)(cb0 + ro * 64 + 4); tsa = *(const f32x4*)(sb0 + ro * 64); tsb = *(const f32x4*)(sb0 + ro * 64 + 4); }
;                 EPI_SCHED();
;             }
;             u32x4 w1, w2; w1.x = pk2(v1[0], v1[1]); w1.y = pk2(v1[2], v1[3]); w1.z = pk2(v1[4], v1[5]); w1.w = pk2(v1[6], v1[7]);
;             w2.x = pk2(v2[0], v2[1]); w2.y = pk2(v2[2], v2[3]); w2.z = pk2(v2[4], v2[5]); w2.w = pk2(v2[6], v2[7]);
;             bf16_t* p = base + (size_t)row * ATW + head * 128 + c0;
;             *(u32x4*)p = w1; *(u32x4*)(p + 64) = w2;
.LBB0_579:
	v_cvt_pk_bf16_f32 v35, v38, v39
	s_waitcnt vmcnt(3)
	v_fmamk_f32 v38, v99, 0x3a800000, v226
	v_mul_f32_e32 v39, 0x4b800000, v38
	v_cmp_gt_f32_e32 vcc, s33, v38
	v_cvt_pk_bf16_f32 v74, v74, v75
	v_cvt_pk_bf16_f32 v75, v72, v73
	v_cndmask_b32_e32 v38, v38, v39, vcc
	v_rsq_f32_e32 v38, v38
	v_cvt_pk_bf16_f32 v76, v46, v47
	v_cvt_pk_bf16_f32 v77, v40, v41
	v_cvt_pk_bf16_f32 v36, v36, v37
	v_cvt_pk_bf16_f32 v37, v32, v33
	v_mad_i64_i32 v[32:33], s[34:35], v51, s80, v[144:145]
	v_cvt_pk_bf16_f32 v34, v44, v45
	global_store_dwordx4 v[32:33], v[74:77], off
	global_store_dwordx4 v[32:33], v[34:37], off offset:128
	v_mul_f32_e32 v32, 0x45800000, v38
	v_cndmask_b32_e32 v38, v38, v32, vcc
	v_pk_mul_f32 v[34:35], v[28:29], v[38:39] op_sel_hi:[1,0]
	v_pk_mul_f32 v[28:29], v[20:21], v[38:39] op_sel_hi:[1,0]
	v_pk_mul_f32 v[20:21], v[16:17], v[38:39] op_sel_hi:[1,0]
	v_mul_f32_e32 v16, v18, v38
	v_mov_b32_e32 v18, v27
	v_add_u32_e32 v36, 0xa0, v182
	v_pk_mul_f32 v[32:33], v[30:31], v[38:39] op_sel_hi:[1,0]
	v_pk_mul_f32 v[22:23], v[22:23], v[38:39] op_sel_hi:[1,0]
	v_pk_mul_f32 v[30:31], v[24:25], v[38:39] op_sel_hi:[1,0]
	v_mul_f32_e32 v24, v26, v38
	s_and_b64 vcc, exec, s[4:5]
	v_pk_mul_f32 v[18:19], v[18:19], v[38:39] op_sel_hi:[1,0]
	s_cbranch_vccnz .LBB0_583
	v_pk_mul_f32 v[26:27], v[28:29], v[28:29]
	v_pk_mul_f32 v[38:39], v[22:23], v[22:23]
	v_pk_fma_f32 v[26:27], v[34:35], v[34:35], v[26:27]
	v_pk_fma_f32 v[38:39], v[32:33], v[32:33], v[38:39]
	v_add_f32_e32 v17, v26, v27
	v_pk_mul_f32 v[40:41], v[20:21], v[20:21]
	v_add_f32_e32 v17, v38, v17
	v_pk_fma_f32 v[40:41], v[30:31], v[30:31], v[40:41]
	v_add_f32_e32 v17, v39, v17
	v_add_f32_e32 v17, v40, v17
	v_mul_f32_e32 v25, v16, v16
	v_add_f32_e32 v17, v41, v17
	v_fmac_f32_e32 v25, v24, v24
	v_pk_mul_f32 v[26:27], v[18:19], v[18:19]
	v_add_f32_e32 v17, v25, v17
	v_add_f32_e32 v25, v26, v27
	v_add_f32_e32 v17, v25, v17
	ds_bpermute_b32 v25, v207, v17
	s_waitcnt lgkmcnt(0)
	v_add_f32_e32 v17, v17, v25
	ds_bpermute_b32 v25, v208, v17
	s_and_saveexec_b64 s[34:35], s[0:1]
	s_cbranch_execz .LBB0_582
	v_mov_b64_e32 v[26:27], s[14:15]
	v_mad_i64_i32 v[26:27], s[50:51], v36, s63, v[26:27]
	v_lshl_add_u64 v[26:27], s[30:31], 2, v[26:27]
	s_waitcnt lgkmcnt(0)
	v_add_f32_e32 v17, v17, v25
	v_lshl_add_u64 v[26:27], s[28:29], 2, v[26:27]
	v_mov_b32_e32 v224, v17
.LBB0_582:
	s_or_b64 exec, exec, s[34:35]
	v_pk_mul_f32 v[28:29], v[56:57], v[28:29]
	v_pk_mul_f32 v[26:27], v[60:61], v[34:35]
	s_waitcnt vmcnt(2)
	v_pk_mul_f32 v[34:35], v[28:29], v[92:93]
	v_pk_mul_f32 v[28:29], v[28:29], v[68:69]
	v_mul_f32_e32 v17, v54, v24
	v_mul_f32_e32 v16, v50, v16
	v_pk_mul_f32 v[22:23], v[58:59], v[22:23]
	v_pk_mul_f32 v[20:21], v[48:49], v[20:21]
	v_mul_f32_e32 v24, v17, v66
	s_waitcnt vmcnt(1)
	v_mul_f32_e32 v42, v16, v90
	v_mul_f32_e32 v16, v16, v66
	v_mul_f32_e32 v44, v17, v90
	v_pk_mul_f32 v[18:19], v[180:181], v[18:19]
	v_mov_b32_e32 v66, v91
	v_pk_fma_f32 v[28:29], v[26:27], v[92:93], v[28:29]
	v_mov_b32_e32 v90, v67
	v_pk_fma_f32 v[34:35], v[26:27], v[68:69], v[34:35] neg_lo:[0,0,1] neg_hi:[0,0,1]
	v_add_co_u32_e32 v26, vcc, s66, v186
	v_pk_mul_f32 v[32:33], v[62:63], v[32:33]
	v_pk_mul_f32 v[38:39], v[22:23], v[94:95]
	v_pk_mul_f32 v[22:23], v[22:23], v[70:71]
	v_pk_mul_f32 v[30:31], v[52:53], v[30:31]
	v_pk_mul_f32 v[40:41], v[20:21], v[88:89]
	v_pk_mul_f32 v[20:21], v[20:21], v[64:65]
	v_pk_mul_f32 v[46:47], v[18:19], v[66:67]
	v_pk_mul_f32 v[18:19], v[18:19], v[90:91]
	v_addc_co_u32_e32 v27, vcc, 0, v187, vcc
	v_pk_fma_f32 v[22:23], v[32:33], v[94:95], v[22:23]
	v_pk_fma_f32 v[20:21], v[30:31], v[88:89], v[20:21]
	s_waitcnt lgkmcnt(0)
	v_mov_b32_e32 v25, v18
	v_mov_b32_e32 v43, v19
	v_pk_fma_f32 v[32:33], v[32:33], v[70:71], v[38:39] neg_lo:[0,0,1] neg_hi:[0,0,1]
	v_pk_fma_f32 v[30:31], v[30:31], v[64:65], v[40:41] neg_lo:[0,0,1] neg_hi:[0,0,1]
	v_lshl_add_u64 v[18:19], v[186:187], 0, s[82:83]
	global_load_dwordx4 v[68:71], v[26:27], off
	global_load_dwordx4 v[64:67], v[18:19], off offset:16
	v_add_co_u32_e32 v26, vcc, s66, v184
	v_lshl_add_u64 v[18:19], v[184:185], 0, s[82:83]
	s_nop 0
	v_addc_co_u32_e32 v27, vcc, 0, v185, vcc
	global_load_dwordx4 v[92:95], v[26:27], off
	global_load_dwordx4 v[88:91], v[18:19], off offset:16
	v_mov_b32_e32 v45, v46
	v_mov_b32_e32 v17, v47
	v_pk_add_f32 v[16:17], v[44:45], v[16:17]
	v_pk_add_f32 v[24:25], v[24:25], v[42:43] neg_lo:[0,1] neg_hi:[0,1]
	s_branch .LBB0_584

; __device__ __forceinline__ float shx(float v, int lane, int mask) { return __int_as_float(__builtin_amdgcn_ds_bpermute((lane ^ mask) << 2, __float_as_int(v))); }
; #define EPI_SCHED() do {} while (0)
;     __device__ __forceinline__ void operator()(const AccT& acc, const Unit& u, int wr, int wc, int fr, int fq) const {
;     ...
;         for (int idx = 0; idx < 8; ++idx) {
;             const int ai = idx >> 2, m = idx & 3, rofs = ai * 128 + m * 16;
;             const int row = row0 + rofs; const float rs = rsqrtf(rsn[idx & 1] * (1.f / 1024.f) + EPS);
;             if (idx + 2 < 8) rsn[idx & 1] = ssq[row0 + ((idx + 2) >> 2) * 128 + ((idx + 2) & 3) * 16];
;             float v1[8], v2[8];
; #pragma unroll
;             for (int n = 0; n < 2; ++n)
; #pragma unroll
;                 for (int j = 0; j < 4; ++j) { v1[n * 4 + j] = acc[ai][0][m][n][j] * rs; v2[n * 4 + j] = acc[ai][1][m][n][j] * rs; }
;             if (rope) {
;                 float s = 0.f;
; #pragma unroll
;                 for (int e = 0; e < 8; ++e) s += v1[e] * v1[e] + v2[e] * v2[e];
;                 s += shx(s, LANE_, 16); s += shx(s, LANE_, 32);
;                 if (fq == 0) atomicAdd(hssq + (size_t)row * 24 + seg * 12 + head, s);
; #pragma unroll
;                 for (int e = 0; e < 8; ++e) {
;                     const float cs = e < 4 ? tca[e & 3] : tcb[e & 3], sn = e < 4 ? tsa[e & 3] : tsb[e & 3];
;                     const float y1 = v1[e] * (e < 4 ? g1a[e & 3] : g1b[e & 3]), y2 = v2[e] * (e < 4 ? g2a[e & 3] : g2b[e & 3]);
;                     v1[e] = y1 * cs - y2 * sn; v2[e] = y2 * cs + y1 * sn;
;                 }
;                 EPI_SCHED();
;                 if (idx + 1 < 8) { const int ro = ((idx + 1) >> 2) * 128 + ((idx + 1) & 3) * 16;
;                     tca = *(const f32x4*)(cb0 + ro * 64); tcb = *(const f32x4*)(cb0 + ro * 64 + 4); tsa = *(const f32x4*)(sb0 + ro * 64); tsb = *(const f32x4*)(sb0 + ro * 64 + 4); }
;                 EPI_SCHED();
;             }
.LBB0_584:
	v_cvt_pk_bf16_f32 v19, v22, v23
	s_waitcnt vmcnt(2)
	v_fmamk_f32 v22, v55, 0x3a800000, v226
	v_mul_f32_e32 v23, 0x4b800000, v22
	v_cmp_gt_f32_e32 vcc, s33, v22
	v_cvt_pk_bf16_f32 v38, v34, v35
	v_cvt_pk_bf16_f32 v39, v32, v33
	v_cndmask_b32_e32 v22, v22, v23, vcc
	v_rsq_f32_e32 v22, v22
	v_cvt_pk_bf16_f32 v40, v30, v31
	v_cvt_pk_bf16_f32 v41, v24, v25
	v_cvt_pk_bf16_f32 v20, v20, v21
	v_cvt_pk_bf16_f32 v21, v16, v17
	v_mad_i64_i32 v[16:17], s[34:35], v36, s80, v[144:145]
	v_cvt_pk_bf16_f32 v18, v28, v29
	global_store_dwordx4 v[16:17], v[38:41], off
	global_store_dwordx4 v[16:17], v[18:21], off offset:128
	v_mul_f32_e32 v16, 0x45800000, v22
	v_cndmask_b32_e32 v22, v22, v16, vcc
	v_pk_mul_f32 v[16:17], v[12:13], v[22:23] op_sel_hi:[1,0]
	v_pk_mul_f32 v[12:13], v[14:15], v[22:23] op_sel_hi:[1,0]
	v_pk_mul_f32 v[14:15], v[6:7], v[22:23] op_sel_hi:[1,0]
	v_mul_f32_e32 v6, v2, v22
	v_mov_b32_e32 v2, v11
	v_add_u32_e32 v20, 0xb0, v182
	v_pk_mul_f32 v[18:19], v[4:5], v[22:23] op_sel_hi:[1,0]
	v_pk_mul_f32 v[4:5], v[8:9], v[22:23] op_sel_hi:[1,0]
	v_pk_mul_f32 v[8:9], v[0:1], v[22:23] op_sel_hi:[1,0]
	v_mul_f32_e32 v0, v10, v22
	s_and_b64 vcc, exec, s[4:5]
	v_pk_mul_f32 v[2:3], v[2:3], v[22:23] op_sel_hi:[1,0]
	s_cbranch_vccnz .LBB0_588
	v_pk_mul_f32 v[10:11], v[18:19], v[18:19]
	v_pk_mul_f32 v[22:23], v[14:15], v[14:15]
	v_pk_fma_f32 v[10:11], v[16:17], v[16:17], v[10:11]
	v_pk_fma_f32 v[22:23], v[12:13], v[12:13], v[22:23]
	v_add_f32_e32 v1, v10, v11
	v_pk_mul_f32 v[24:25], v[8:9], v[8:9]
	v_add_f32_e32 v1, v22, v1
	v_pk_fma_f32 v[24:25], v[4:5], v[4:5], v[24:25]
	v_add_f32_e32 v1, v23, v1
	v_add_f32_e32 v1, v24, v1
	v_mul_f32_e32 v7, v6, v6
	v_add_f32_e32 v1, v25, v1
	v_fmac_f32_e32 v7, v0, v0
	v_pk_mul_f32 v[10:11], v[2:3], v[2:3]
	v_add_f32_e32 v1, v7, v1
	v_add_f32_e32 v7, v10, v11
	v_add_f32_e32 v1, v7, v1
	ds_bpermute_b32 v7, v207, v1
	s_waitcnt lgkmcnt(0)
	v_add_f32_e32 v1, v1, v7
	ds_bpermute_b32 v7, v208, v1
	s_and_saveexec_b64 s[4:5], s[0:1]
	s_cbranch_execz .LBB0_587
	v_mov_b64_e32 v[10:11], s[14:15]
	v_mad_i64_i32 v[10:11], s[34:35], v20, s63, v[10:11]
	v_lshl_add_u64 v[10:11], s[30:31], 2, v[10:11]
	s_waitcnt lgkmcnt(0)
	v_add_f32_e32 v1, v1, v7
	v_lshl_add_u64 v[10:11], s[28:29], 2, v[10:11]
	v_mov_b32_e32 v227, v1
.LBB0_587:
	s_or_b64 exec, exec, s[4:5]
	v_mul_f32_e32 v1, v54, v0
	s_waitcnt lgkmcnt(0)
	v_mul_f32_e32 v7, v50, v6
	v_mul_f32_e32 v0, v1, v66
	s_waitcnt vmcnt(1)
	v_mul_f32_e32 v6, v7, v90
	v_mul_f32_e32 v26, v7, v66
	v_mul_f32_e32 v28, v1, v90
	v_pk_mul_f32 v[2:3], v[180:181], v[2:3]
	v_mov_b32_e32 v90, v67
	v_mov_b32_e32 v66, v91
	v_pk_mul_f32 v[10:11], v[60:61], v[16:17]
	v_pk_mul_f32 v[16:17], v[56:57], v[18:19]
	v_pk_mul_f32 v[22:23], v[62:63], v[12:13]
	v_pk_mul_f32 v[12:13], v[58:59], v[14:15]
	v_pk_mul_f32 v[24:25], v[52:53], v[4:5]
	v_pk_mul_f32 v[4:5], v[48:49], v[8:9]
	v_pk_mul_f32 v[30:31], v[2:3], v[90:91]
	v_pk_mul_f32 v[2:3], v[2:3], v[66:67]
	v_pk_mul_f32 v[18:19], v[16:17], v[68:69]
	v_pk_mul_f32 v[16:17], v[16:17], v[92:93]
	v_pk_mul_f32 v[14:15], v[12:13], v[70:71]
	v_pk_mul_f32 v[12:13], v[12:13], v[94:95]
	v_pk_mul_f32 v[8:9], v[4:5], v[64:65]
	v_pk_mul_f32 v[4:5], v[4:5], v[88:89]
	v_mov_b32_e32 v1, v30
	v_mov_b32_e32 v7, v31
	v_mov_b32_e32 v29, v2
	v_mov_b32_e32 v27, v3
	v_pk_fma_f32 v[16:17], v[10:11], v[68:69], v[16:17] neg_lo:[0,0,1] neg_hi:[0,0,1]
	v_pk_fma_f32 v[12:13], v[22:23], v[70:71], v[12:13] neg_lo:[0,0,1] neg_hi:[0,0,1]
	v_pk_fma_f32 v[4:5], v[24:25], v[64:65], v[4:5] neg_lo:[0,0,1] neg_hi:[0,0,1]
	v_pk_add_f32 v[0:1], v[0:1], v[6:7] neg_lo:[0,1] neg_hi:[0,1]
	v_pk_fma_f32 v[18:19], v[10:11], v[92:93], v[18:19]
	v_pk_fma_f32 v[14:15], v[22:23], v[94:95], v[14:15]
	v_pk_fma_f32 v[8:9], v[24:25], v[88:89], v[8:9]
	v_pk_add_f32 v[6:7], v[28:29], v[26:27]
	s_branch .LBB0_589

; __device__ __forceinline__ unsigned pk2(float lo, float hi) { f32x2 v = {lo, hi}; bf2_t b = __builtin_convertvector(v, bf2_t); return __builtin_bit_cast(unsigned, b); }
; __device__ __forceinline__ float shx(float v, int lane, int mask) { return __int_as_float(__builtin_amdgcn_ds_bpermute((lane ^ mask) << 2, __float_as_int(v))); }
;     __device__ __forceinline__ void operator()(const AccT& acc, const Unit& u, int wr, int wc, int fr, int fq) const {
;     ...
;                 s += shx(s, LANE_, 16); s += shx(s, LANE_, 32);
;                 if (fq == 0) atomicAdd(hssq + (size_t)row * 24 + seg * 12 + head, s);
;     ...
;             u32x4 w1, w2; w1.x = pk2(v1[0], v1[1]); w1.y = pk2(v1[2], v1[3]); w1.z = pk2(v1[4], v1[5]); w1.w = pk2(v1[6], v1[7]);
;             w2.x = pk2(v2[0], v2[1]); w2.y = pk2(v2[2], v2[3]); w2.z = pk2(v2[4], v2[5]); w2.w = pk2(v2[6], v2[7]);
;             bf16_t* p = base + (size_t)row * ATW + head * 128 + c0;
;             *(u32x4*)p = w1; *(u32x4*)(p + 64) = w2;
.LBB0_589:
	v_cvt_pk_bf16_f32 v2, v16, v17
	v_cvt_pk_bf16_f32 v3, v12, v13
	v_cvt_pk_bf16_f32 v4, v4, v5
	v_cvt_pk_bf16_f32 v5, v0, v1
	v_mad_i64_i32 v[0:1], s[4:5], v20, s80, v[144:145]
	s_andn2_b64 vcc, exec, s[2:3]
	s_mov_b64 s[2:3], -1
	v_cvt_pk_bf16_f32 v10, v18, v19
	v_cvt_pk_bf16_f32 v11, v14, v15
	v_cvt_pk_bf16_f32 v12, v8, v9
	v_cvt_pk_bf16_f32 v13, v6, v7
	global_store_dwordx4 v[0:1], v[2:5], off
	global_store_dwordx4 v[0:1], v[10:13], off offset:128
	s_cmp_eq_u64 s[58:59], 0
	s_cbranch_scc0 .Lpb_noatom
	s_and_saveexec_b64 s[52:53], s[0:1]
	v_mov_b32_e32 v228, v182
	v_mov_b64_e32 v[234:235], s[14:15]
	v_mad_i64_i32 v[234:235], s[54:55], v228, s63, v[234:235]
	v_lshl_add_u64 v[234:235], s[30:31], 2, v[234:235]
	v_lshl_add_u64 v[234:235], s[28:29], 2, v[234:235]
	global_atomic_add_f32 v[234:235], v218, off
	v_add_u32_e32 v228, 0x10, v182
	v_mov_b64_e32 v[234:235], s[14:15]
	v_mad_i64_i32 v[234:235], s[54:55], v228, s63, v[234:235]
	v_lshl_add_u64 v[234:235], s[30:31], 2, v[234:235]
	v_lshl_add_u64 v[234:235], s[28:29], 2, v[234:235]
	global_atomic_add_f32 v[234:235], v219, off
	v_add_u32_e32 v228, 0x20, v182
	v_mov_b64_e32 v[234:235], s[14:15]
	v_mad_i64_i32 v[234:235], s[54:55], v228, s63, v[234:235]
	v_lshl_add_u64 v[234:235], s[30:31], 2, v[234:235]
	v_lshl_add_u64 v[234:235], s[28:29], 2, v[234:235]
	global_atomic_add_f32 v[234:235], v220, off
	v_add_u32_e32 v228, 0x30, v182
	v_mov_b64_e32 v[234:235], s[14:15]
	v_mad_i64_i32 v[234:235], s[54:55], v228, s63, v[234:235]
	v_lshl_add_u64 v[234:235], s[30:31], 2, v[234:235]
	v_lshl_add_u64 v[234:235], s[28:29], 2, v[234:235]
	global_atomic_add_f32 v[234:235], v221, off
	v_add_u32_e32 v228, 0x80, v182
	v_mov_b64_e32 v[234:235], s[14:15]
	v_mad_i64_i32 v[234:235], s[54:55], v228, s63, v[234:235]
	v_lshl_add_u64 v[234:235], s[30:31], 2, v[234:235]
	v_lshl_add_u64 v[234:235], s[28:29], 2, v[234:235]
	global_atomic_add_f32 v[234:235], v222, off
	v_add_u32_e32 v228, 0x90, v182
	v_mov_b64_e32 v[234:235], s[14:15]
	v_mad_i64_i32 v[234:235], s[54:55], v228, s63, v[234:235]
	v_lshl_add_u64 v[234:235], s[30:31], 2, v[234:235]
	v_lshl_add_u64 v[234:235], s[28:29], 2, v[234:235]
	global_atomic_add_f32 v[234:235], v223, off
	v_add_u32_e32 v228, 0xa0, v182
	v_mov_b64_e32 v[234:235], s[14:15]
	v_mad_i64_i32 v[234:235], s[54:55], v228, s63, v[234:235]
	v_lshl_add_u64 v[234:235], s[30:31], 2, v[234:235]
	v_lshl_add_u64 v[234:235], s[28:29], 2, v[234:235]
	global_atomic_add_f32 v[234:235], v224, off
	v_add_u32_e32 v228, 0xb0, v182
	v_mov_b64_e32 v[234:235], s[14:15]
	v_mad_i64_i32 v[234:235], s[54:55], v228, s63, v[234:235]
	v_lshl_add_u64 v[234:235], s[30:31], 2, v[234:235]
	v_lshl_add_u64 v[234:235], s[28:29], 2, v[234:235]
	global_atomic_add_f32 v[234:235], v227, off
	s_mov_b64 exec, s[52:53]
.Lpb_noatom:
	s_cbranch_vccnz .LBB0_538
	s_andn2_b64 vcc, exec, s[6:7]
	s_cbranch_vccnz .LBB0_537
	s_barrier
	s_branch .LBB0_537
